# S5 scan MODE 0: the 15 look-ahead u tiles of a direction staged by LDS-DMA into the wave's own LDS slab before the step loop (ds_read per step instead of a global load per step)
# baseline (speedup 1.0000x reference)
; #define VM_WAIT() asm volatile("s_waitcnt vmcnt(0)" ::: "memory")
; template <int MODE, int DIR> __device__ __forceinline__ void s5_dir(const Args& a, int l, int lane, int tok0, int gr, LAS unsigned char* st, bf16* yf) {
;     ...
;     const int n = lane & 15, g = lane >> 4, dg = DIR * 32 + gr, ch = tok0 / SCH + g;
;     pg8::bf16x8 bbf[8], cf[4];
;     { const pg8::bf16x8* bp = (const pg8::bf16x8*)(a.ws + WS_TBBF) + (size_t)dg * 8 * 64 + lane;
; #pragma unroll
;       for (int c = 0; c < 8; ++c) bbf[c] = bp[c * 64]; }
;     if (MODE) { const pg8::bf16x8* cp = (const pg8::bf16x8*)(a.ws + WS_TCF) + (size_t)dg * 4 * 64 + lane;
; #pragma unroll
;       for (int c = 0; c < 4; ++c) cf[c] = cp[c * 64]; }
;     float lbr[4], lbi[4], sr[4], si[4];
; #pragma unroll
;     for (int cb = 0; cb < 4; ++cb) { const size_t ix = ((size_t)dg * 64 + 16 * cb + n) * 2; lbr[cb] = TLB[ix]; lbi[cb] = TLB[ix + 1];
;         if (MODE) { const size_t cx = ((((size_t)ch * 2 + DIR) * 32 + gr) * 64 + 16 * cb + n) * 2; sr[cb] = CIN[cx]; si[cb] = CIN[cx + 1]; } else { sr[cb] = 0.f; si[cb] = 0.f; } }
;     const float dsk = MODE ? a.in[I_SD][(size_t)l * 512 + 16 * gr + n] : 0.f;
;     const bf16* ua = Z + (size_t)(tok0 + (n >> 2) * SCH + (n & 3)) * ZRW + RXS + 16 * gr + 8 * (g & 1);
;     bf16* yo = YG + (size_t)(tok0 + g * SCH) * 512 + 16 * gr + n;
;     const bf16* xo = Z + (size_t)(tok0 + g * SCH) * ZRW + RXS + 16 * gr + n;
;     constexpr int NST = SCH / 4, T0 = DIR ? (SCH - 4) : 0, DT = DIR ? -4 : 4;
;     pg8::bf16x8 un = *(const pg8::bf16x8*)(ua + (size_t)T0 * ZRW);
;     unsigned short ygn[4], xsn[4];
;     if (MODE && DIR) {
;         VM_WAIT();
; #pragma unroll
;         for (int rg = 0; rg < 4; ++rg) { ygn[rg] = yf[((T0 >> 2) * 4 + rg) * 64 + lane]; xsn[rg] = xo[(size_t)(T0 + rg) * ZRW]; } }
; #pragma unroll 1
;     for (int step = 0; step < NST; ++step) {
;         const int t4 = T0 + DT * step;
;         const pg8::bf16x8 u8 = un; unsigned short ygc[4], xsc[4];
;         if (MODE && DIR) {
; #pragma unroll
;             for (int rg = 0; rg < 4; ++rg) { ygc[rg] = ygn[rg]; xsc[rg] = xsn[rg]; } }
;         if (step + 1 < NST) { un = *(const pg8::bf16x8*)(ua + (size_t)(t4 + DT) * ZRW);
.LBB0_462:
	s_or_b64 exec, exec, s[38:39]
	v_readfirstlane_b32 s0, v10
	s_cmp_ge_i32 s0, s27
	s_mov_b64 s[36:37], -1
	s_cbranch_scc1 .LBB0_457
	s_cmp_ge_i32 s0, s25
	s_cbranch_scc0 .LBB0_473
	s_add_i32 s4, s0, s12
	s_and_b32 s1, s4, 31
	s_lshl_b32 s82, s1, 13
	s_lshl_b32 s4, s4, 3
	v_lshl_add_u64 v[26:27], v[128:129], 0, s[82:83]
	s_lshl_b32 s5, s1, 6
	s_and_b32 s4, s4, 0xffffff00
	v_add_co_u32_e32 v38, vcc, 0x1000, v26
	v_or_b32_e32 v42, s5, v126
	v_readlane_b32 s6, v249, 48
	v_addc_co_u32_e32 v39, vcc, 0, v27, vcc
	v_lshlrev_b32_e32 v42, 3, v42
	v_readlane_b32 s7, v249, 49
	v_or_b32_e32 v46, s4, v127
	s_movk_i32 s8, 0xc00
	v_mov_b64_e32 v[44:45], s[90:91]
	global_load_dwordx4 v[10:13], v[26:27], off
	global_load_dwordx4 v[14:17], v[26:27], off offset:1024
	global_load_dwordx4 v[18:21], v[26:27], off offset:2048
	global_load_dwordx4 v[22:25], v[26:27], off offset:3072
	s_nop 0
	global_load_dwordx4 v[26:29], v[38:39], off
	global_load_dwordx4 v[30:33], v[38:39], off offset:1024
	global_load_dwordx4 v[34:37], v[38:39], off offset:2048
	s_nop 0
	global_load_dwordx4 v[38:41], v[38:39], off offset:3072
	s_nop 0
	global_load_dwordx2 v[52:53], v42, s[6:7]
	global_load_dwordx2 v[54:55], v42, s[6:7] offset:128
	global_load_dwordx2 v[56:57], v42, s[6:7] offset:256
	global_load_dwordx2 v[58:59], v42, s[6:7] offset:384
	v_mad_i64_i32 v[44:45], s[6:7], v46, s8, v[44:45]
	s_lshl_b32 s82, s1, 5
	v_mad_i64_i32 v[42:43], s[6:7], v46, s8, 0
	v_lshl_add_u64 v[44:45], v[44:45], 0, s[82:83]
	v_mov_b32_e32 v137, v191
	v_lshl_add_u64 v[44:45], v[44:45], 0, v[136:137]
	s_mov_b64 s[6:7], 0x1f000800
	v_lshl_add_u64 v[50:51], v[44:45], 0, s[6:7]
	s_mov_b32 s6, 0x1f000000
	v_add_co_u32_e32 v44, vcc, s6, v44
	s_add_i32 s6, s15, s0
	s_nop 0
	v_addc_co_u32_e32 v45, vcc, 0, v45, vcc
	global_load_dwordx4 v[46:49], v[44:45], off offset:2048
	s_and_b32 s6, s6, 31
	v_lshl_or_b32 v42, s6, 5, v42
	v_lshl_add_u64 v[68:69], v[134:135], 0, v[42:43]
	v_mov_b32_e32 v70, 0
	s_movk_i32 s30, 0xc00
	s_mov_b64 s[38:39], 0
	v_readfirstlane_b32 s100, v0
	s_nop 0
	s_lshr_b32 s100, s100, 6
	s_lshl_b32 s100, s100, 14
	s_mov_b32 m0, s100
	v_lshl_add_u64 v[42:43], v[68:69], 0, s[38:39]
	global_load_lds_dwordx4 v[42:43], off
	s_add_u32 s38, s38, 0x3000
	s_add_i32 m0, s100, 0x400
	v_lshl_add_u64 v[42:43], v[68:69], 0, s[38:39]
	global_load_lds_dwordx4 v[42:43], off
	s_add_u32 s38, s38, 0x3000
	s_add_i32 m0, s100, 0x800
	v_lshl_add_u64 v[42:43], v[68:69], 0, s[38:39]
	global_load_lds_dwordx4 v[42:43], off
	s_add_u32 s38, s38, 0x3000
	s_add_i32 m0, s100, 0xc00
	v_lshl_add_u64 v[42:43], v[68:69], 0, s[38:39]
	global_load_lds_dwordx4 v[42:43], off
	s_add_u32 s38, s38, 0x3000
	s_add_i32 m0, s100, 0x1000
	v_lshl_add_u64 v[42:43], v[68:69], 0, s[38:39]
	global_load_lds_dwordx4 v[42:43], off
	s_add_u32 s38, s38, 0x3000
	s_add_i32 m0, s100, 0x1400
	v_lshl_add_u64 v[42:43], v[68:69], 0, s[38:39]
	global_load_lds_dwordx4 v[42:43], off
	s_add_u32 s38, s38, 0x3000
	s_add_i32 m0, s100, 0x1800
	v_lshl_add_u64 v[42:43], v[68:69], 0, s[38:39]
	global_load_lds_dwordx4 v[42:43], off
	s_add_u32 s38, s38, 0x3000
	s_add_i32 m0, s100, 0x1c00
	v_lshl_add_u64 v[42:43], v[68:69], 0, s[38:39]
	global_load_lds_dwordx4 v[42:43], off
	s_add_u32 s38, s38, 0x3000
	s_add_i32 m0, s100, 0x2000
	v_lshl_add_u64 v[42:43], v[68:69], 0, s[38:39]
	global_load_lds_dwordx4 v[42:43], off
	s_add_u32 s38, s38, 0x3000
	s_add_i32 m0, s100, 0x2400
	v_lshl_add_u64 v[42:43], v[68:69], 0, s[38:39]
	global_load_lds_dwordx4 v[42:43], off
	s_add_u32 s38, s38, 0x3000
	s_add_i32 m0, s100, 0x2800
	v_lshl_add_u64 v[42:43], v[68:69], 0, s[38:39]
	global_load_lds_dwordx4 v[42:43], off
	s_add_u32 s38, s38, 0x3000
	s_add_i32 m0, s100, 0x2c00
	v_lshl_add_u64 v[42:43], v[68:69], 0, s[38:39]
	global_load_lds_dwordx4 v[42:43], off
	s_add_u32 s38, s38, 0x3000
	s_add_i32 m0, s100, 0x3000
	v_lshl_add_u64 v[42:43], v[68:69], 0, s[38:39]
	global_load_lds_dwordx4 v[42:43], off
	s_add_u32 s38, s38, 0x3000
	s_add_i32 m0, s100, 0x3400
	v_lshl_add_u64 v[42:43], v[68:69], 0, s[38:39]
	global_load_lds_dwordx4 v[42:43], off
	s_add_u32 s38, s38, 0x3000
	s_add_i32 m0, s100, 0x3800
	v_lshl_add_u64 v[42:43], v[68:69], 0, s[38:39]
	global_load_lds_dwordx4 v[42:43], off
	s_add_u32 s38, s38, 0x3000
	s_mov_b64 s[38:39], 0
	s_mov_b32 s101, s100
	v_mov_b32_e32 v71, v70
	v_mov_b32_e32 v72, v70
	v_mov_b32_e32 v73, v70
	v_mov_b32_e32 v74, v70
	v_mov_b32_e32 v75, v70
	v_mov_b32_e32 v76, v70
	v_mov_b32_e32 v77, v70
	s_waitcnt vmcnt(19)
	v_pk_mov_b32 v[66:67], v[52:53], v[52:53] op_sel:[1,0]
	s_waitcnt vmcnt(18)
	v_pk_mov_b32 v[64:65], v[54:55], v[54:55] op_sel:[1,0]
	s_waitcnt vmcnt(17)
	v_pk_mov_b32 v[62:63], v[56:57], v[56:57] op_sel:[1,0]
	s_waitcnt vmcnt(16)
	v_pk_mov_b32 v[60:61], v[58:59], v[58:59] op_sel:[1,0]
	s_waitcnt vmcnt(15)
	v_mov_b64_e32 v[42:43], v[46:47]
	v_mov_b64_e32 v[44:45], v[48:49]
	s_waitcnt vmcnt(0)
	s_branch .LBB0_466
; template <int MODE, int DIR> __device__ __forceinline__ void s5_dir(const Args& a, int l, int lane, int tok0, int gr, LAS unsigned char* st, bf16* yf) {
;     ...
;         if (step + 1 < NST) { un = *(const pg8::bf16x8*)(ua + (size_t)(t4 + DT) * ZRW);
;             if (MODE && DIR) {
; #pragma unroll
;                 for (int rg = 0; rg < 4; ++rg) { ygn[rg] = yf[(((t4 + DT) >> 2) * 4 + rg) * 64 + lane]; xsn[rg] = xo[(size_t)(t4 + DT + rg) * ZRW]; } } }
;         f32x4 in[8];
; #pragma unroll
;         for (int c = 0; c < 8; ++c) in[c] = __builtin_amdgcn_mfma_f32_16x16x32_bf16(u8, bbf[c], (f32x4){0.f, 0.f, 0.f, 0.f}, 0, 0, 0);
;         float str[4][4], sti[4][4];
; #pragma unroll
;         for (int rr = 0; rr < 4; ++rr) { const int rg = DIR ? 3 - rr : rr;
; #pragma unroll
;             for (int cb = 0; cb < 4; ++cb) { const float nr = lbr[cb] * sr[cb] - lbi[cb] * si[cb] + in[cb][rg], ni = lbr[cb] * si[cb] + lbi[cb] * sr[cb] + in[4 + cb][rg];
;                 sr[cb] = nr; si[cb] = ni; str[cb][rg] = nr; sti[cb][rg] = ni; } }
.LBB0_465:
	v_pk_mul_f32 v[80:81], v[52:53], v[76:77]
	v_pk_mul_f32 v[82:83], v[66:67], v[76:77]
	v_mfma_f32_16x16x32_bf16 v[76:79], v[46:49], v[10:13], 0
	v_sub_f32_e32 v80, v80, v81
	v_add_f32_e32 v84, v82, v83
	v_pk_mul_f32 v[92:93], v[56:57], v[72:73]
	v_pk_mul_f32 v[72:73], v[62:63], v[72:73]
	v_pk_mul_f32 v[100:101], v[58:59], v[70:71]
	s_nop 2
	v_add_f32_e32 v76, v80, v76
	v_mfma_f32_16x16x32_bf16 v[80:83], v[46:49], v[26:29], 0
	v_add_f32_e32 v72, v72, v73
	v_sub_f32_e32 v73, v100, v101
	v_pk_mul_f32 v[70:71], v[60:61], v[70:71]
	v_mfma_f32_16x16x32_bf16 v[96:99], v[46:49], v[34:37], 0
	v_add_f32_e32 v70, v70, v71
	s_nop 2
	v_add_f32_e32 v80, v84, v80
	v_pk_mul_f32 v[84:85], v[54:55], v[74:75]
	v_pk_mul_f32 v[74:75], v[64:65], v[74:75]
	v_sub_f32_e32 v88, v84, v85
	v_mfma_f32_16x16x32_bf16 v[84:87], v[46:49], v[14:17], 0
	v_add_f32_e32 v74, v74, v75
	v_sub_f32_e32 v75, v92, v93
	v_add_f32_e32 v72, v72, v96
	v_mfma_f32_16x16x32_bf16 v[92:95], v[46:49], v[18:21], 0
	s_add_u32 s38, s38, 0x3000
	s_nop 2
	v_add_f32_e32 v84, v88, v84
	s_addc_u32 s39, s39, 0
	v_mfma_f32_16x16x32_bf16 v[88:91], v[46:49], v[30:33], 0
	s_cmp_lg_u32 s38, 0x30000
	v_add_f32_e32 v92, v75, v92
	v_mov_b32_e32 v96, v93
	v_mfma_f32_16x16x32_bf16 v[100:103], v[46:49], v[22:25], 0
	v_mfma_f32_16x16x32_bf16 v[46:49], v[46:49], v[38:41], 0
	s_nop 2
	v_add_f32_e32 v74, v74, v88
	v_pk_mul_f32 v[74:75], v[64:65], v[74:75] op_sel_hi:[1,0]
	v_mov_b32_e32 v88, v85
	s_nop 0
	v_add_f32_e32 v100, v73, v100
	v_add_f32_e32 v46, v70, v46
	v_pk_mul_f32 v[70:71], v[66:67], v[80:81] op_sel_hi:[1,0]
	v_mov_b32_e32 v80, v77
	v_pk_fma_f32 v[104:105], v[52:53], v[76:77], v[70:71] neg_lo:[0,0,1] neg_hi:[0,0,1]
	v_pk_fma_f32 v[70:71], v[52:53], v[76:77], v[70:71] op_sel_hi:[1,0,1]
	s_nop 0
	v_mov_b32_e32 v105, v71
	v_pk_add_f32 v[70:71], v[80:81], v[104:105]
	v_pk_fma_f32 v[80:81], v[54:55], v[84:85], v[74:75] neg_lo:[0,0,1] neg_hi:[0,0,1]
	v_pk_fma_f32 v[74:75], v[54:55], v[84:85], v[74:75] op_sel_hi:[1,0,1]
	v_pk_mul_f32 v[76:77], v[52:53], v[70:71]
	v_mov_b32_e32 v81, v75
	v_sub_f32_e32 v73, v76, v77
	v_pk_add_f32 v[74:75], v[88:89], v[80:81]
	v_add_f32_e32 v76, v78, v73
	v_pk_mul_f32 v[70:71], v[66:67], v[70:71]
	v_pk_mul_f32 v[80:81], v[54:55], v[74:75]
	v_pk_mul_f32 v[72:73], v[62:63], v[72:73] op_sel_hi:[1,0]
	v_add_f32_e32 v70, v70, v71
	v_sub_f32_e32 v71, v80, v81
	v_pk_fma_f32 v[80:81], v[56:57], v[92:93], v[72:73] neg_lo:[0,0,1] neg_hi:[0,0,1]
	v_pk_fma_f32 v[72:73], v[56:57], v[92:93], v[72:73] op_sel_hi:[1,0,1]
	v_pk_mul_f32 v[84:85], v[60:61], v[46:47] op_sel_hi:[1,0]
	v_mov_b32_e32 v81, v73
	v_pk_mul_f32 v[74:75], v[64:65], v[74:75]
	v_pk_add_f32 v[72:73], v[96:97], v[80:81]
	v_pk_fma_f32 v[88:89], v[58:59], v[100:101], v[84:85] neg_lo:[0,0,1] neg_hi:[0,0,1]
	v_pk_fma_f32 v[84:85], v[58:59], v[100:101], v[84:85] op_sel_hi:[1,0,1]
	v_add_f32_e32 v78, v86, v71
	v_add_f32_e32 v71, v74, v75
	v_pk_mul_f32 v[80:81], v[56:57], v[72:73]
	v_mov_b32_e32 v89, v85
	v_mov_b32_e32 v46, v101
	v_add_f32_e32 v74, v90, v71
	v_sub_f32_e32 v71, v80, v81
	v_pk_mul_f32 v[72:73], v[62:63], v[72:73]
	v_pk_add_f32 v[46:47], v[46:47], v[88:89]
	v_add_f32_e32 v80, v94, v71
	v_add_f32_e32 v71, v72, v73
	v_pk_mul_f32 v[84:85], v[58:59], v[46:47]
	v_add_f32_e32 v70, v82, v70
	v_add_f32_e32 v72, v98, v71
	v_sub_f32_e32 v71, v84, v85
	v_add_f32_e32 v84, v102, v71
	v_pk_mul_f32 v[70:71], v[66:67], v[70:71] op_sel_hi:[1,0]
	v_pk_mul_f32 v[46:47], v[60:61], v[46:47]
	v_pk_fma_f32 v[88:89], v[52:53], v[76:77], v[70:71] neg_lo:[0,0,1] neg_hi:[0,0,1]
	v_pk_fma_f32 v[70:71], v[52:53], v[76:77], v[70:71] op_sel_hi:[1,0,1]
	v_add_f32_e32 v46, v46, v47
	v_mov_b32_e32 v89, v71
	v_pk_mul_f32 v[70:71], v[64:65], v[74:75] op_sel_hi:[1,0]
	v_add_f32_e32 v46, v48, v46
	v_pk_fma_f32 v[74:75], v[54:55], v[78:79], v[70:71] neg_lo:[0,0,1] neg_hi:[0,0,1]
	v_pk_fma_f32 v[70:71], v[54:55], v[78:79], v[70:71] op_sel_hi:[1,0,1]
	v_pk_mul_f32 v[46:47], v[60:61], v[46:47] op_sel_hi:[1,0]
	v_mov_b32_e32 v75, v71
	v_pk_mul_f32 v[70:71], v[62:63], v[72:73] op_sel_hi:[1,0]
	v_mov_b32_e32 v48, v103
	v_pk_fma_f32 v[72:73], v[56:57], v[80:81], v[70:71] neg_lo:[0,0,1] neg_hi:[0,0,1]
	v_pk_fma_f32 v[70:71], v[56:57], v[80:81], v[70:71] op_sel_hi:[1,0,1]
	v_mov_b32_e32 v82, v79
	v_mov_b32_e32 v73, v71
	v_pk_fma_f32 v[70:71], v[58:59], v[84:85], v[46:47] neg_lo:[0,0,1] neg_hi:[0,0,1]
	v_pk_fma_f32 v[46:47], v[58:59], v[84:85], v[46:47] op_sel_hi:[1,0,1]
	v_mov_b32_e32 v90, v87
	v_mov_b32_e32 v71, v47
	v_mov_b32_e32 v98, v95
	v_pk_add_f32 v[70:71], v[48:49], v[70:71]
	s_waitcnt lgkmcnt(0)
	v_mov_b64_e32 v[48:49], v[44:45]
	v_pk_add_f32 v[76:77], v[82:83], v[88:89]
	v_pk_add_f32 v[74:75], v[90:91], v[74:75]
	v_pk_add_f32 v[72:73], v[98:99], v[72:73]
	v_mov_b64_e32 v[46:47], v[42:43]
	s_cbranch_scc0 .LBB0_468
.LBB0_466:
	s_cmp_eq_u32 s38, 0x2d000
	s_cbranch_scc1 .LBB0_465
	v_and_b32_e32 v42, 63, v0
	v_lshl_add_u32 v42, v42, 4, s101
	ds_read_b128 v[42:45], v42
	s_addk_i32 s101, 0x400
	s_branch .LBB0_465
; template <int MODE, int DIR> __device__ __forceinline__ void s5_dir(const Args& a, int l, int lane, int tok0, int gr, LAS unsigned char* st, bf16* yf) {
;     ...
;     const int n = lane & 15, g = lane >> 4, dg = DIR * 32 + gr, ch = tok0 / SCH + g;
;     pg8::bf16x8 bbf[8], cf[4];
;     { const pg8::bf16x8* bp = (const pg8::bf16x8*)(a.ws + WS_TBBF) + (size_t)dg * 8 * 64 + lane;
; #pragma unroll
;       for (int c = 0; c < 8; ++c) bbf[c] = bp[c * 64]; }
;     if (MODE) { const pg8::bf16x8* cp = (const pg8::bf16x8*)(a.ws + WS_TCF) + (size_t)dg * 4 * 64 + lane;
; #pragma unroll
;       for (int c = 0; c < 4; ++c) cf[c] = cp[c * 64]; }
;     float lbr[4], lbi[4], sr[4], si[4];
; #pragma unroll
;     for (int cb = 0; cb < 4; ++cb) { const size_t ix = ((size_t)dg * 64 + 16 * cb + n) * 2; lbr[cb] = TLB[ix]; lbi[cb] = TLB[ix + 1];
;         if (MODE) { const size_t cx = ((((size_t)ch * 2 + DIR) * 32 + gr) * 64 + 16 * cb + n) * 2; sr[cb] = CIN[cx]; si[cb] = CIN[cx + 1]; } else { sr[cb] = 0.f; si[cb] = 0.f; } }
;     const float dsk = MODE ? a.in[I_SD][(size_t)l * 512 + 16 * gr + n] : 0.f;
;     const bf16* ua = Z + (size_t)(tok0 + (n >> 2) * SCH + (n & 3)) * ZRW + RXS + 16 * gr + 8 * (g & 1);
;     bf16* yo = YG + (size_t)(tok0 + g * SCH) * 512 + 16 * gr + n;
;     const bf16* xo = Z + (size_t)(tok0 + g * SCH) * ZRW + RXS + 16 * gr + n;
;     constexpr int NST = SCH / 4, T0 = DIR ? (SCH - 4) : 0, DT = DIR ? -4 : 4;
;     pg8::bf16x8 un = *(const pg8::bf16x8*)(ua + (size_t)T0 * ZRW);
;     ...
;     if (!MODE) {
; #pragma unroll
;         for (int cb = 0; cb < 4; ++cb) { const size_t cx = ((((size_t)ch * 2 + DIR) * 32 + gr) * 64 + 16 * cb + n) * 2; E[cx] = sr[cb]; E[cx + 1] = si[cb]; } }
.LBB0_468:
	s_ashr_i32 s4, s4, 6
	v_or_b32_e32 v10, s4, v1
	v_ashrrev_i32_e32 v11, 31, v10
	v_lshlrev_b64 v[52:53], 12, v[10:11]
	v_or3_b32 v10, s5, v52, v126
	v_readlane_b32 s4, v252, 38
	v_or3_b32 v11, 0, v53, 0
	v_readlane_b32 s5, v252, 39
	s_nop 1
	v_lshl_add_u64 v[10:11], v[10:11], 3, s[4:5]
	s_or_b32 s4, s1, 32
	s_lshl_b32 s82, s4, 13
	v_lshl_add_u64 v[26:27], v[128:129], 0, s[82:83]
	s_movk_i32 s5, 0x1000
	v_add_co_u32_e32 v38, vcc, s5, v26
	s_lshl_b32 s82, s4, 9
	global_store_dwordx2 v[10:11], v[76:77], off
	global_store_dwordx2 v[10:11], v[74:75], off offset:128
	global_store_dwordx2 v[10:11], v[72:73], off offset:256
	global_store_dwordx2 v[10:11], v[70:71], off offset:384
	v_addc_co_u32_e32 v39, vcc, 0, v27, vcc
	v_lshl_add_u64 v[34:35], v[130:131], 0, s[82:83]
	global_load_dwordx4 v[10:13], v[26:27], off
	global_load_dwordx4 v[14:17], v[26:27], off offset:1024
	global_load_dwordx4 v[18:21], v[26:27], off offset:2048
	global_load_dwordx4 v[22:25], v[26:27], off offset:3072
	s_nop 0
	global_load_dwordx4 v[26:29], v[38:39], off
	global_load_dwordx4 v[30:33], v[38:39], off offset:1024
	global_load_dwordx2 v[54:55], v[34:35], off
	global_load_dwordx2 v[56:57], v[34:35], off offset:128
	global_load_dwordx2 v[58:59], v[34:35], off offset:256
	global_load_dwordx2 v[60:61], v[34:35], off offset:384
	v_add_co_u32_e32 v34, vcc, 0x2d000, v50
	v_mov_b32_e32 v70, 0
	s_nop 0
	v_addc_co_u32_e32 v35, vcc, 0, v51, vcc
	global_load_dwordx4 v[46:49], v[34:35], off
	s_nop 0
	global_load_dwordx4 v[34:37], v[38:39], off offset:2048
	s_nop 0
	global_load_dwordx4 v[38:41], v[38:39], off offset:3072
	v_mov_b32_e32 v71, v70
	v_mov_b32_e32 v74, v70
	v_mov_b32_e32 v75, v70
	v_mov_b32_e32 v72, v70
	v_mov_b32_e32 v73, v70
	v_mov_b32_e32 v76, v70
	v_mov_b32_e32 v77, v70
	s_mov_b32 s82, 0x15000
	s_mov_b32 m0, s100
	v_lshl_add_u64 v[42:43], s[82:83], 1, v[50:51]
	global_load_lds_dwordx4 v[42:43], off
	s_addk_i32 s82, 0xe800
	s_add_i32 m0, s100, 0x400
	v_lshl_add_u64 v[42:43], s[82:83], 1, v[50:51]
	global_load_lds_dwordx4 v[42:43], off
	s_addk_i32 s82, 0xe800
	s_add_i32 m0, s100, 0x800
	v_lshl_add_u64 v[42:43], s[82:83], 1, v[50:51]
	global_load_lds_dwordx4 v[42:43], off
	s_addk_i32 s82, 0xe800
	s_add_i32 m0, s100, 0xc00
	v_lshl_add_u64 v[42:43], s[82:83], 1, v[50:51]
	global_load_lds_dwordx4 v[42:43], off
	s_addk_i32 s82, 0xe800
	s_add_i32 m0, s100, 0x1000
	v_lshl_add_u64 v[42:43], s[82:83], 1, v[50:51]
	global_load_lds_dwordx4 v[42:43], off
	s_addk_i32 s82, 0xe800
	s_add_i32 m0, s100, 0x1400
	v_lshl_add_u64 v[42:43], s[82:83], 1, v[50:51]
	global_load_lds_dwordx4 v[42:43], off
	s_addk_i32 s82, 0xe800
	s_add_i32 m0, s100, 0x1800
	v_lshl_add_u64 v[42:43], s[82:83], 1, v[50:51]
	global_load_lds_dwordx4 v[42:43], off
	s_addk_i32 s82, 0xe800
	s_add_i32 m0, s100, 0x1c00
	v_lshl_add_u64 v[42:43], s[82:83], 1, v[50:51]
	global_load_lds_dwordx4 v[42:43], off
	s_addk_i32 s82, 0xe800
	s_add_i32 m0, s100, 0x2000
	v_lshl_add_u64 v[42:43], s[82:83], 1, v[50:51]
	global_load_lds_dwordx4 v[42:43], off
	s_addk_i32 s82, 0xe800
	s_add_i32 m0, s100, 0x2400
	v_lshl_add_u64 v[42:43], s[82:83], 1, v[50:51]
	global_load_lds_dwordx4 v[42:43], off
	s_addk_i32 s82, 0xe800
	s_add_i32 m0, s100, 0x2800
	v_lshl_add_u64 v[42:43], s[82:83], 1, v[50:51]
	global_load_lds_dwordx4 v[42:43], off
	s_addk_i32 s82, 0xe800
	s_add_i32 m0, s100, 0x2c00
	v_lshl_add_u64 v[42:43], s[82:83], 1, v[50:51]
	global_load_lds_dwordx4 v[42:43], off
	s_addk_i32 s82, 0xe800
	s_add_i32 m0, s100, 0x3000
	v_lshl_add_u64 v[42:43], s[82:83], 1, v[50:51]
	global_load_lds_dwordx4 v[42:43], off
	s_addk_i32 s82, 0xe800
	s_add_i32 m0, s100, 0x3400
	v_lshl_add_u64 v[42:43], s[82:83], 1, v[50:51]
	global_load_lds_dwordx4 v[42:43], off
	s_addk_i32 s82, 0xe800
	s_add_i32 m0, s100, 0x3800
	v_lshl_add_u64 v[42:43], s[82:83], 1, v[50:51]
	global_load_lds_dwordx4 v[42:43], off
	s_addk_i32 s82, 0xe800
	s_mov_b32 s82, 0x15000
	s_mov_b32 s101, s100
	s_waitcnt vmcnt(21)
	v_pk_mov_b32 v[68:69], v[54:55], v[54:55] op_sel:[1,0]
	s_waitcnt vmcnt(20)
	v_pk_mov_b32 v[66:67], v[56:57], v[56:57] op_sel:[1,0]
	s_waitcnt vmcnt(19)
	v_pk_mov_b32 v[64:65], v[58:59], v[58:59] op_sel:[1,0]
	s_waitcnt vmcnt(18)
	v_pk_mov_b32 v[62:63], v[60:61], v[60:61] op_sel:[1,0]
	s_waitcnt vmcnt(17)
	v_mov_b64_e32 v[42:43], v[46:47]
	v_mov_b64_e32 v[44:45], v[48:49]
	s_waitcnt vmcnt(0)
	s_branch .LBB0_470
; template <int MODE, int DIR> __device__ __forceinline__ void s5_dir(const Args& a, int l, int lane, int tok0, int gr, LAS unsigned char* st, bf16* yf) {
;     ...
;         if (step + 1 < NST) { un = *(const pg8::bf16x8*)(ua + (size_t)(t4 + DT) * ZRW);
;             if (MODE && DIR) {
; #pragma unroll
;                 for (int rg = 0; rg < 4; ++rg) { ygn[rg] = yf[(((t4 + DT) >> 2) * 4 + rg) * 64 + lane]; xsn[rg] = xo[(size_t)(t4 + DT + rg) * ZRW]; } } }
;         f32x4 in[8];
; #pragma unroll
;         for (int c = 0; c < 8; ++c) in[c] = __builtin_amdgcn_mfma_f32_16x16x32_bf16(u8, bbf[c], (f32x4){0.f, 0.f, 0.f, 0.f}, 0, 0, 0);
;         float str[4][4], sti[4][4];
; #pragma unroll
;         for (int rr = 0; rr < 4; ++rr) { const int rg = DIR ? 3 - rr : rr;
; #pragma unroll
;             for (int cb = 0; cb < 4; ++cb) { const float nr = lbr[cb] * sr[cb] - lbi[cb] * si[cb] + in[cb][rg], ni = lbr[cb] * si[cb] + lbi[cb] * sr[cb] + in[4 + cb][rg];
;                 sr[cb] = nr; si[cb] = ni; str[cb][rg] = nr; sti[cb][rg] = ni; } }
.LBB0_469:
	v_pk_mul_f32 v[80:81], v[54:55], v[76:77]
	v_pk_mul_f32 v[82:83], v[68:69], v[76:77]
	v_mfma_f32_16x16x32_bf16 v[76:79], v[46:49], v[10:13], 0
	v_mul_f32_e64 v84, v56, v72
	v_mul_f32_e64 v85, v57, v73
	v_pk_mul_f32 v[72:73], v[66:67], v[72:73]
	v_pk_mul_f32 v[92:93], v[58:59], v[74:75]
	v_sub_f32_e32 v80, v80, v81
	v_add_f32_e32 v72, v72, v73
	v_sub_f32_e32 v73, v92, v93
	v_mfma_f32_16x16x32_bf16 v[92:95], v[46:49], v[18:21], 0
	v_add_f32_e32 v104, v80, v79
	v_add_f32_e32 v79, v82, v83
	v_pk_mul_f32 v[74:75], v[64:65], v[74:75]
	v_mfma_f32_16x16x32_bf16 v[80:83], v[46:49], v[26:29], 0
	v_mul_f32_e64 v100, v60, v70
	v_mul_f32_e64 v101, v61, v71
	s_nop 1
	v_add_f32_e32 v110, v73, v95
	v_add_f32_e32 v73, v74, v75
	s_waitcnt vmcnt(1)
	v_mfma_f32_16x16x32_bf16 v[96:99], v[46:49], v[34:37], 0
	v_mul_f32_e64 v70, v62, v70
	v_mul_f32_e64 v71, v63, v71
	v_add_f32_e32 v106, v79, v83
	v_sub_f32_e32 v79, v84, v85
	v_mfma_f32_16x16x32_bf16 v[88:91], v[46:49], v[30:33], 0
	v_pk_mul_f32 v[106:107], v[68:69], v[106:107] op_sel_hi:[1,0]
	s_nop 1
	v_add_f32_e32 v74, v73, v99
	v_sub_f32_e32 v73, v100, v101
	v_mfma_f32_16x16x32_bf16 v[84:87], v[46:49], v[14:17], 0
	v_fma_f32 v114, v54, v104, -v106
	v_fma_f32 v115, v55, v105, -v107
	v_add_f32_e32 v72, v72, v91
	v_pk_fma_f32 v[104:105], v[54:55], v[104:105], v[106:107] op_sel_hi:[1,0,1]
	v_mfma_f32_16x16x32_bf16 v[100:103], v[46:49], v[22:25], 0
	v_mov_b32_e32 v115, v105
	s_nop 1
	v_add_f32_e32 v108, v79, v87
	v_mov_b32_e32 v79, v82
	s_waitcnt vmcnt(0)
	v_mfma_f32_16x16x32_bf16 v[46:49], v[46:49], v[38:41], 0
	v_add_f32_e64 v78, v78, v114
	v_add_f32_e64 v79, v79, v115
	v_add_f32_e32 v112, v73, v103
	v_pk_mul_f32 v[72:73], v[66:67], v[72:73] op_sel_hi:[1,0]
	v_add_f32_e32 v70, v70, v71
	v_pk_fma_f32 v[104:105], v[56:57], v[108:109], v[72:73] neg_lo:[0,0,1] neg_hi:[0,0,1]
	v_pk_fma_f32 v[72:73], v[56:57], v[108:109], v[72:73] op_sel_hi:[1,0,1]
	v_pk_mul_f32 v[82:83], v[54:55], v[78:79]
	v_mov_b32_e32 v105, v73
	v_mov_b32_e32 v87, v90
	v_pk_mul_f32 v[74:75], v[64:65], v[74:75] op_sel_hi:[1,0]
	v_add_f32_e32 v70, v70, v49
	v_sub_f32_e32 v49, v82, v83
	v_pk_mul_f32 v[78:79], v[68:69], v[78:79]
	v_pk_add_f32 v[72:73], v[86:87], v[104:105]
	v_pk_fma_f32 v[90:91], v[58:59], v[110:111], v[74:75] neg_lo:[0,0,1] neg_hi:[0,0,1]
	v_pk_fma_f32 v[74:75], v[58:59], v[110:111], v[74:75] op_sel_hi:[1,0,1]
	v_add_f32_e32 v82, v77, v49
	v_add_f32_e32 v49, v78, v79
	v_pk_mul_f32 v[86:87], v[56:57], v[72:73]
	v_mov_b32_e32 v91, v75
	v_mov_b32_e32 v95, v98
	v_add_f32_e32 v78, v81, v49
	v_sub_f32_e32 v49, v86, v87
	v_pk_mul_f32 v[72:73], v[66:67], v[72:73]
	v_pk_add_f32 v[74:75], v[94:95], v[90:91]
	v_add_f32_e32 v86, v85, v49
	v_add_f32_e32 v49, v72, v73
	v_pk_mul_f32 v[90:91], v[58:59], v[74:75]
	v_pk_mul_f32 v[70:71], v[62:63], v[70:71] op_sel_hi:[1,0]
	v_add_f32_e32 v72, v89, v49
	v_sub_f32_e32 v49, v90, v91
	v_pk_mul_f32 v[74:75], v[64:65], v[74:75]
	v_pk_fma_f32 v[94:95], v[60:61], v[112:113], v[70:71] neg_lo:[0,0,1] neg_hi:[0,0,1]
	v_pk_fma_f32 v[70:71], v[60:61], v[112:113], v[70:71] op_sel_hi:[1,0,1]
	v_add_f32_e32 v90, v93, v49
	v_add_f32_e32 v49, v74, v75
	v_mov_b32_e32 v95, v71
	v_mov_b32_e32 v103, v48
	v_pk_mul_f32 v[78:79], v[68:69], v[78:79] op_sel_hi:[1,0]
	v_add_f32_e32 v74, v97, v49
	v_pk_add_f32 v[48:49], v[102:103], v[94:95]
	v_pk_fma_f32 v[94:95], v[54:55], v[82:83], v[78:79] neg_lo:[0,0,1] neg_hi:[0,0,1]
	v_pk_fma_f32 v[78:79], v[54:55], v[82:83], v[78:79] op_sel_hi:[1,0,1]
	v_pk_mul_f32 v[72:73], v[66:67], v[72:73] op_sel_hi:[1,0]
	v_pk_mul_f32 v[70:71], v[60:61], v[48:49]
	v_pk_mul_f32 v[48:49], v[62:63], v[48:49]
	v_mov_b32_e32 v95, v79
	v_pk_fma_f32 v[78:79], v[56:57], v[86:87], v[72:73] neg_lo:[0,0,1] neg_hi:[0,0,1]
	v_pk_fma_f32 v[72:73], v[56:57], v[86:87], v[72:73] op_sel_hi:[1,0,1]
	v_add_f32_e32 v48, v48, v49
	v_mov_b32_e32 v79, v73
	v_mov_b32_e32 v85, v88
	v_pk_mul_f32 v[74:75], v[64:65], v[74:75] op_sel_hi:[1,0]
	v_sub_f32_e32 v70, v70, v71
	v_add_f32_e32 v48, v47, v48
	v_pk_add_f32 v[72:73], v[84:85], v[78:79]
	v_pk_fma_f32 v[78:79], v[58:59], v[90:91], v[74:75] neg_lo:[0,0,1] neg_hi:[0,0,1]
	v_pk_fma_f32 v[74:75], v[58:59], v[90:91], v[74:75] op_sel_hi:[1,0,1]
	v_add_f32_e32 v70, v101, v70
	v_mov_b32_e32 v79, v75
	v_mov_b32_e32 v93, v96
	v_pk_mul_f32 v[48:49], v[62:63], v[48:49] op_sel_hi:[1,0]
	v_pk_add_f32 v[74:75], v[92:93], v[78:79]
	v_pk_fma_f32 v[78:79], v[60:61], v[70:71], v[48:49] neg_lo:[0,0,1] neg_hi:[0,0,1]
	v_pk_fma_f32 v[48:49], v[60:61], v[70:71], v[48:49] op_sel_hi:[1,0,1]
	v_mov_b32_e32 v77, v80
	v_mov_b32_e32 v79, v49
	v_mov_b32_e32 v101, v46
	s_addk_i32 s82, 0xe800
	s_waitcnt lgkmcnt(0)
	v_mov_b64_e32 v[48:49], v[44:45]
	v_pk_add_f32 v[76:77], v[76:77], v[94:95]
	v_pk_add_f32 v[70:71], v[100:101], v[78:79]
	s_cmpk_lg_i32 s82, 0xd000
	v_mov_b64_e32 v[46:47], v[42:43]
	s_cbranch_scc0 .LBB0_472
.LBB0_470:
	s_cmpk_eq_i32 s82, 0xe800
	s_cbranch_scc1 .LBB0_469
	v_and_b32_e32 v42, 63, v0
	v_lshl_add_u32 v42, v42, 4, s101
	ds_read_b128 v[42:45], v42
	s_addk_i32 s101, 0x400
	s_branch .LBB0_469

; __global__ void __launch_bounds__(NTHR, 2) mk_fwd(Args args) {
	.amdhsa_kernel _Z6mk_fwd4Args
		.amdhsa_group_segment_fixed_size 0
		.amdhsa_private_segment_fixed_size 0
		.amdhsa_kernarg_size 504
		.amdhsa_user_sgpr_count 2
		.amdhsa_user_sgpr_dispatch_ptr 0
		.amdhsa_user_sgpr_queue_ptr 0
		.amdhsa_user_sgpr_kernarg_segment_ptr 1
		.amdhsa_user_sgpr_dispatch_id 0
		.amdhsa_user_sgpr_kernarg_preload_length 0
		.amdhsa_user_sgpr_kernarg_preload_offset 0
		.amdhsa_user_sgpr_private_segment_size 0
		.amdhsa_uses_dynamic_stack 0
		.amdhsa_enable_private_segment 0
		.amdhsa_system_sgpr_workgroup_id_x 1
		.amdhsa_system_sgpr_workgroup_id_y 0
		.amdhsa_system_sgpr_workgroup_id_z 0
		.amdhsa_system_sgpr_workgroup_info 0
		.amdhsa_system_vgpr_workitem_id 0
		.amdhsa_next_free_vgpr 256
		.amdhsa_next_free_sgpr 102
		.amdhsa_accum_offset 256
		.amdhsa_reserve_vcc 1
		.amdhsa_float_round_mode_32 0
		.amdhsa_float_round_mode_16_64 0
		.amdhsa_float_denorm_mode_32 3
		.amdhsa_float_denorm_mode_16_64 3
		.amdhsa_dx10_clamp 1
		.amdhsa_ieee_mode 1
		.amdhsa_fp16_overflow 0
		.amdhsa_tg_split 0
		.amdhsa_exception_fp_ieee_invalid_op 0
		.amdhsa_exception_fp_denorm_src 0
		.amdhsa_exception_fp_ieee_div_zero 0
		.amdhsa_exception_fp_ieee_overflow 0
		.amdhsa_exception_fp_ieee_underflow 0
		.amdhsa_exception_fp_ieee_inexact 0
		.amdhsa_exception_int_div_zero 0
	.end_amdhsa_kernel

; __global__ void __launch_bounds__(NTHR, 2) mk_fwd(Args args) {
amdhsa.kernels:
  - .agpr_count:     0
    .args:
      - .offset:         0
        .size:           248
        .value_kind:     by_value
      - .offset:         248
        .size:           4
        .value_kind:     hidden_block_count_x
      - .offset:         252
        .size:           4
        .value_kind:     hidden_block_count_y
      - .offset:         256
        .size:           4
        .value_kind:     hidden_block_count_z
      - .offset:         260
        .size:           2
        .value_kind:     hidden_group_size_x
      - .offset:         262
        .size:           2
        .value_kind:     hidden_group_size_y
      - .offset:         264
        .size:           2
        .value_kind:     hidden_group_size_z
      - .offset:         266
        .size:           2
        .value_kind:     hidden_remainder_x
      - .offset:         268
        .size:           2
        .value_kind:     hidden_remainder_y
      - .offset:         270
        .size:           2
        .value_kind:     hidden_remainder_z
      - .offset:         288
        .size:           8
        .value_kind:     hidden_global_offset_x
      - .offset:         296
        .size:           8
        .value_kind:     hidden_global_offset_y
      - .offset:         304
        .size:           8
        .value_kind:     hidden_global_offset_z
      - .offset:         312
        .size:           2
        .value_kind:     hidden_grid_dims
      - .offset:         368
        .size:           4
        .value_kind:     hidden_dynamic_lds_size
    .group_segment_fixed_size: 0
    .kernarg_segment_align: 8
    .kernarg_segment_size: 504
    .language:       OpenCL C
    .language_version:
      - 2
      - 0
    .max_flat_workgroup_size: 512
    .name:           _Z6mk_fwd4Args
    .private_segment_fixed_size: 0
    .sgpr_count:     108
    .sgpr_spill_count: 483
    .symbol:         _Z6mk_fwd4Args.kd
    .uniform_work_group_size: 1
    .uses_dynamic_stack: false
    .vgpr_count:     256
    .vgpr_spill_count: 0
    .wavefront_size: 64
